# unrolled serial load-wait loops (lru weights, sgu masked weights) and hoisted sgu gain loads ahead of the stores
# baseline (speedup 1.0000x reference)
; __device__ __forceinline__ unsigned short f2bf(float f) { return (unsigned short)(cvt_pk_bf16(f, 0.f) & 0xffffu); }
; __device__ __forceinline__ void lru_pass1(CArgs& a, LAS unsigned char* lds, int layer, int item, const bf16* z, float* LH, float* LP, float* LE) {
;     ...
;     { const float* wa = a.in[I_WA] + ((size_t)layer * 4 + blk) * 4096; const float* wx = a.in[I_WX] + ((size_t)layer * 4 + blk) * 4096;
;       for (int e = tid; e < 4096; e += NTHREADS) { const int i = e >> 6, j = e & 63; WaT[j * SLD + i] = f2bf(wa[e]); WxT[j * SLD + i] = f2bf(wx[e]); } }
.LBB0_184:
	global_load_dword v10, v[4:5], off
	global_load_dword v18, v[2:3], off
	v_lshl_add_u64 v[4:5], v[4:5], 0, s[90:91]
	v_lshl_add_u64 v[2:3], v[2:3], 0, s[90:91]
	global_load_dword v11, v[4:5], off
	global_load_dword v19, v[2:3], off
	v_lshl_add_u64 v[4:5], v[4:5], 0, s[90:91]
	v_lshl_add_u64 v[2:3], v[2:3], 0, s[90:91]
	global_load_dword v12, v[4:5], off
	global_load_dword v20, v[2:3], off
	v_lshl_add_u64 v[4:5], v[4:5], 0, s[90:91]
	v_lshl_add_u64 v[2:3], v[2:3], 0, s[90:91]
	global_load_dword v13, v[4:5], off
	global_load_dword v21, v[2:3], off
	v_lshl_add_u64 v[4:5], v[4:5], 0, s[90:91]
	v_lshl_add_u64 v[2:3], v[2:3], 0, s[90:91]
	global_load_dword v14, v[4:5], off
	global_load_dword v22, v[2:3], off
	v_lshl_add_u64 v[4:5], v[4:5], 0, s[90:91]
	v_lshl_add_u64 v[2:3], v[2:3], 0, s[90:91]
	global_load_dword v15, v[4:5], off
	global_load_dword v23, v[2:3], off
	v_lshl_add_u64 v[4:5], v[4:5], 0, s[90:91]
	v_lshl_add_u64 v[2:3], v[2:3], 0, s[90:91]
	global_load_dword v16, v[4:5], off
	global_load_dword v24, v[2:3], off
	v_lshl_add_u64 v[4:5], v[4:5], 0, s[90:91]
	v_lshl_add_u64 v[2:3], v[2:3], 0, s[90:91]
	global_load_dword v17, v[4:5], off
	global_load_dword v25, v[2:3], off
	v_ashrrev_i32_e32 v7, 6, v0
	v_add_u32_e32 v7, v7, v6
	v_lshl_add_u32 v7, v7, 1, 0
	s_waitcnt vmcnt(14)
	v_cvt_pk_bf16_f32 v10, v10, s0
	v_cvt_pk_bf16_f32 v18, v18, s0
	ds_write_b16 v7, v10
	ds_write_b16 v7, v18 offset:9216
	s_waitcnt vmcnt(12)
	v_cvt_pk_bf16_f32 v11, v11, s0
	v_cvt_pk_bf16_f32 v19, v19, s0
	ds_write_b16 v7, v11 offset:16
	ds_write_b16 v7, v19 offset:9232
	s_waitcnt vmcnt(10)
	v_cvt_pk_bf16_f32 v12, v12, s0
	v_cvt_pk_bf16_f32 v20, v20, s0
	ds_write_b16 v7, v12 offset:32
	ds_write_b16 v7, v20 offset:9248
	s_waitcnt vmcnt(8)
	v_cvt_pk_bf16_f32 v13, v13, s0
	v_cvt_pk_bf16_f32 v21, v21, s0
	ds_write_b16 v7, v13 offset:48
	ds_write_b16 v7, v21 offset:9264
	s_waitcnt vmcnt(6)
	v_cvt_pk_bf16_f32 v14, v14, s0
	v_cvt_pk_bf16_f32 v22, v22, s0
	ds_write_b16 v7, v14 offset:64
	ds_write_b16 v7, v22 offset:9280
	s_waitcnt vmcnt(4)
	v_cvt_pk_bf16_f32 v15, v15, s0
	v_cvt_pk_bf16_f32 v23, v23, s0
	ds_write_b16 v7, v15 offset:80
	ds_write_b16 v7, v23 offset:9296
	s_waitcnt vmcnt(2)
	v_cvt_pk_bf16_f32 v16, v16, s0
	v_cvt_pk_bf16_f32 v24, v24, s0
	ds_write_b16 v7, v16 offset:96
	ds_write_b16 v7, v24 offset:9312
	s_waitcnt vmcnt(0)
	v_cvt_pk_bf16_f32 v17, v17, s0
	v_cvt_pk_bf16_f32 v25, v25, s0
	ds_write_b16 v7, v17 offset:112
	ds_write_b16 v7, v25 offset:9328

; __device__ __forceinline__ float gelu_t(float x) { return x * fsigmoid(1.5957691216f * (x + 0.044715f * x * x * x)); }
; __device__ __forceinline__ void sgu_items(CArgs& a, LAS unsigned char* lds, int layer, int first, int stride, const bf16* z, bf16* mix) {
;     ...
;         { const int s = tid >> 2, cq = tid & 3; const bf16* vr = z + (t0 + s) * DIN + ZV + grp * 64 + cq * 16;
;           const u32x4 r0 = *(const u32x4*)vr, r1 = *(const u32x4*)(vr + 8);
;           float v[16]; float sum = 0.f;
; #pragma unroll
;           for (int k = 0; k < 4; ++k) { v[2 * k] = gelu_t(__uint_as_float(r0[k] << 16)); v[2 * k + 1] = gelu_t(__uint_as_float(r0[k] & 0xffff0000u));
;               v[8 + 2 * k] = gelu_t(__uint_as_float(r1[k] << 16)); v[8 + 2 * k + 1] = gelu_t(__uint_as_float(r1[k] & 0xffff0000u)); }
; #pragma unroll
;           for (int k = 0; k < 16; ++k) sum += v[k];
;           sum += __shfl_xor(sum, 1); sum += __shfl_xor(sum, 2);
.LBB0_210:
	s_ashr_i32 s8, s14, 2
	s_ashr_i32 s9, s8, 31
	s_lshl_b64 s[8:9], s[8:9], 7
	v_lshl_add_u64 v[2:3], s[8:9], 0, v[26:27]
	v_mov_b64_e32 v[6:7], s[94:95]
	v_mad_u64_u32 v[4:5], s[12:13], v2, s60, v[6:7]
	v_mad_i32_i24 v5, v3, s60, v5
	s_lshl_b32 s62, s15, 7
	v_lshl_add_u64 v[2:3], v[4:5], 0, s[62:63]
	v_mov_b32_e32 v39, v1
	v_lshl_add_u64 v[2:3], v[2:3], 0, v[38:39]
	s_mov_b64 s[12:13], 0x1600
	v_lshl_add_u64 v[4:5], v[2:3], 0, s[12:13]
	v_add_co_u32_e32 v2, vcc, s71, v2
	s_lshl_b32 s12, s15, 9
	s_nop 0
	v_addc_co_u32_e32 v3, vcc, 0, v3, vcc
	global_load_dwordx4 v[8:11], v[2:3], off offset:1536
	s_nop 0
	global_load_dwordx4 v[2:5], v[4:5], off offset:16
	s_mov_b32 s13, s63
	s_add_i32 s14, s14, s52
	s_waitcnt vmcnt(1)
	v_and_b32_e32 v13, 0xffff0000, v8
	v_lshlrev_b32_e32 v0, 16, v8
	v_mul_f32_e32 v8, 0x3d372713, v13
	v_mul_f32_e32 v8, v8, v13
	v_fma_f32 v8, v8, v13, v13
	v_mul_f32_e32 v8, 0x3fcc422a, v8
	v_mul_f32_e32 v8, 0xbfb8aa3b, v8
	v_exp_f32_e32 v8, v8
	v_lshlrev_b32_e32 v15, 16, v9
	v_and_b32_e32 v17, 0xffff0000, v9
	v_lshlrev_b32_e32 v19, 16, v10
	v_add_f32_e32 v8, 1.0, v8
	v_rcp_f32_e32 v14, v8
	v_mul_f32_e32 v8, 0x3d372713, v15
	v_mul_f32_e32 v8, v8, v15
	v_fma_f32 v8, v8, v15, v15
	v_mul_f32_e32 v8, 0x3fcc422a, v8
	v_mul_f32_e32 v8, 0xbfb8aa3b, v8
	v_exp_f32_e32 v8, v8
	v_and_b32_e32 v21, 0xffff0000, v10
	v_lshlrev_b32_e32 v23, 16, v11
	v_and_b32_e32 v25, 0xffff0000, v11
	v_add_f32_e32 v8, 1.0, v8
	v_rcp_f32_e32 v16, v8
	v_mul_f32_e32 v8, 0x3d372713, v17
	v_mul_f32_e32 v8, v8, v17
	v_fma_f32 v8, v8, v17, v17
	v_mul_f32_e32 v8, 0x3fcc422a, v8
	v_mul_f32_e32 v8, 0xbfb8aa3b, v8
	v_exp_f32_e32 v8, v8
	s_waitcnt vmcnt(0)
	v_lshlrev_b32_e32 v49, 16, v3
	v_and_b32_e32 v48, 0xffff0000, v3
	v_mul_f32_e32 v3, 0x3d372713, v49
	v_add_f32_e32 v8, 1.0, v8
	v_rcp_f32_e32 v18, v8
	v_mul_f32_e32 v8, 0x3d372713, v19
	v_mul_f32_e32 v8, v8, v19
	v_fma_f32 v8, v8, v19, v19
	v_mul_f32_e32 v8, 0x3fcc422a, v8
	v_mul_f32_e32 v8, 0xbfb8aa3b, v8
	v_exp_f32_e32 v8, v8
	v_mul_f32_e32 v3, v3, v49
	v_mov_b32_e32 v50, v49
	v_fmac_f32_e32 v50, v3, v50
	v_add_f32_e32 v8, 1.0, v8
	v_rcp_f32_e32 v20, v8
	v_mul_f32_e32 v8, 0x3d372713, v21
	v_mul_f32_e32 v8, v8, v21
	v_fma_f32 v8, v8, v21, v21
	v_mul_f32_e32 v8, 0x3fcc422a, v8
	v_mul_f32_e32 v8, 0xbfb8aa3b, v8
	v_exp_f32_e32 v8, v8
	v_lshlrev_b32_e32 v9, 16, v5
	v_mul_f32_e32 v3, 0x3fcc422a, v50
	v_mul_f32_e32 v3, 0xbfb8aa3b, v3
	v_add_f32_e32 v8, 1.0, v8
	v_rcp_f32_e32 v22, v8
	v_mul_f32_e32 v8, 0x3d372713, v23
	v_mul_f32_e32 v8, v8, v23
	v_fma_f32 v8, v8, v23, v23
	v_mul_f32_e32 v8, 0x3fcc422a, v8
	v_mul_f32_e32 v8, 0xbfb8aa3b, v8
	v_exp_f32_e32 v8, v8
	v_mov_b32_e32 v10, v9
	v_exp_f32_e32 v3, v3
	v_mov_b32_e32 v50, v48
	v_add_f32_e32 v8, 1.0, v8
	v_rcp_f32_e32 v24, v8
	v_mul_f32_e32 v8, 0x3d372713, v25
	v_mul_f32_e32 v8, v8, v25
	v_fma_f32 v8, v8, v25, v25
	v_mul_f32_e32 v8, 0x3fcc422a, v8
	v_mul_f32_e32 v8, 0xbfb8aa3b, v8
	v_exp_f32_e32 v8, v8
	v_add_f32_e32 v3, 1.0, v3
	v_rcp_f32_e32 v51, v3
	v_mul_f32_e32 v3, 0x3d372713, v48
	v_add_f32_e32 v8, 1.0, v8
	v_rcp_f32_e32 v39, v8
	v_and_b32_e32 v8, 0xffff0000, v5
	v_mul_f32_e32 v5, 0x3d372713, v9
	v_mul_f32_e32 v5, v5, v9
	v_fmac_f32_e32 v10, v5, v10
	v_mul_f32_e32 v5, 0x3fcc422a, v10
	v_mul_f32_e32 v5, 0xbfb8aa3b, v5
	v_exp_f32_e32 v5, v5
	v_mul_f32_e32 v3, v3, v48
	v_fmac_f32_e32 v50, v3, v50
	v_mul_f32_e32 v3, 0x3fcc422a, v50
	v_add_f32_e32 v5, 1.0, v5
	v_rcp_f32_e32 v11, v5
	v_mul_f32_e32 v5, 0x3d372713, v8
	v_mul_f32_e32 v3, 0xbfb8aa3b, v3
	v_mul_f32_e32 v5, v5, v8
	v_mov_b32_e32 v10, v8
	v_exp_f32_e32 v3, v3
	v_fmac_f32_e32 v10, v5, v10
	v_mul_f32_e32 v5, 0x3fcc422a, v10
	v_mul_f32_e32 v5, 0xbfb8aa3b, v5
	v_lshlrev_b32_e32 v55, 16, v2
	v_exp_f32_e32 v5, v5
	v_add_f32_e32 v3, 1.0, v3
	v_and_b32_e32 v54, 0xffff0000, v2
	v_mul_f32_e32 v2, 0x3d372713, v55
	v_rcp_f32_e32 v50, v3
	v_mul_f32_e32 v2, v2, v55
	v_mov_b32_e32 v3, v55
	v_fmac_f32_e32 v3, v2, v3
	v_mul_f32_e32 v12, 0x3d372713, v0
	v_lshlrev_b32_e32 v45, 16, v4
	v_mul_f32_e32 v2, 0x3fcc422a, v3
	v_mul_f32_e32 v12, v12, v0
	v_add_f32_e32 v5, 1.0, v5
	v_and_b32_e32 v44, 0xffff0000, v4
	v_mul_f32_e32 v4, 0x3d372713, v45
	v_mul_f32_e32 v2, 0xbfb8aa3b, v2
	v_fma_f32 v12, v12, v0, v0
	v_rcp_f32_e32 v10, v5
	v_mul_f32_e32 v4, v4, v45
	v_mov_b32_e32 v5, v45
	v_exp_f32_e32 v2, v2
	v_mul_f32_e32 v12, 0x3fcc422a, v12
	v_fmac_f32_e32 v5, v4, v5
	v_mul_f32_e32 v12, 0xbfb8aa3b, v12
	v_mul_f32_e32 v4, 0x3fcc422a, v5
	v_exp_f32_e32 v12, v12
	v_mul_f32_e32 v4, 0xbfb8aa3b, v4
	v_exp_f32_e32 v4, v4
	v_add_f32_e32 v2, 1.0, v2
	v_rcp_f32_e32 v3, v2
	v_mul_f32_e32 v2, 0x3d372713, v54
	v_mul_f32_e32 v2, v2, v54
	v_mov_b32_e32 v56, v54
	v_add_f32_e32 v12, 1.0, v12
	v_fmac_f32_e32 v56, v2, v56
	v_rcp_f32_e32 v12, v12
	v_add_f32_e32 v4, 1.0, v4
	v_mul_f32_e32 v2, 0x3fcc422a, v56
	v_rcp_f32_e32 v5, v4
	v_mul_f32_e32 v4, 0x3d372713, v44
	v_mul_f32_e32 v2, 0xbfb8aa3b, v2
	v_mul_f32_e32 v4, v4, v44
	v_mov_b32_e32 v46, v44
	v_exp_f32_e32 v2, v2
	v_fmac_f32_e32 v46, v4, v46
	v_fma_f32 v41, v12, v0, 0
	v_mul_f32_e32 v4, 0x3fcc422a, v46
	v_fmac_f32_e32 v41, v14, v13
	v_mul_f32_e32 v4, 0xbfb8aa3b, v4
	v_fmac_f32_e32 v41, v16, v15
	v_exp_f32_e32 v4, v4
	v_add_f32_e32 v2, 1.0, v2
	v_fmac_f32_e32 v41, v18, v17
	v_rcp_f32_e32 v2, v2
	v_fmac_f32_e32 v41, v20, v19
	v_fmac_f32_e32 v41, v22, v21
	v_fmac_f32_e32 v41, v24, v23
	v_add_f32_e32 v4, 1.0, v4
	v_fmac_f32_e32 v41, v39, v25
	v_rcp_f32_e32 v4, v4
	v_pk_mul_f32 v[56:57], v[2:3], v[54:55]
	v_pk_mul_f32 v[52:53], v[50:51], v[48:49]
	v_add_f32_e32 v41, v57, v41
	v_add_f32_e32 v41, v56, v41
	v_add_f32_e32 v41, v53, v41
	v_pk_mul_f32 v[46:47], v[4:5], v[44:45]
	v_add_f32_e32 v41, v52, v41
	v_add_f32_e32 v41, v47, v41
	v_pk_mul_f32 v[42:43], v[10:11], v[8:9]
	v_add_f32_e32 v41, v46, v41
	v_add_f32_e32 v41, v43, v41
	v_add_f32_e32 v41, v42, v41
	ds_bpermute_b32 v42, v68, v41
	s_waitcnt lgkmcnt(0)
; __device__ __forceinline__ unsigned short f2bf(float f) { return (unsigned short)(cvt_pk_bf16(f, 0.f) & 0xffffu); }
; __device__ __forceinline__ float gelu_t(float x) { return x * fsigmoid(1.5957691216f * (x + 0.044715f * x * x * x)); }
; #define BLOCK_SYNC() do { asm volatile("s_waitcnt lgkmcnt(0)" ::: "memory"); __builtin_amdgcn_s_barrier(); asm volatile("" ::: "memory"); } while (0)
; __device__ __forceinline__ void sgu_items(CArgs& a, LAS unsigned char* lds, int layer, int first, int stride, const bf16* z, bf16* mix) {
;     ...
;           sum += __shfl_xor(sum, 1); sum += __shfl_xor(sum, 2);
;           const float mu = sum * (1.f / 64.f); float sq = 0.f;
; #pragma unroll
;           for (int k = 0; k < 16; ++k) { v[k] -= mu; sq += v[k] * v[k]; }
;           sq += __shfl_xor(sq, 1); sq += __shfl_xor(sq, 2);
;           const float rs = rsqrtf(sq * (1.f / 64.f) + EPS);
; #pragma unroll
;           for (int k = 0; k < 16; ++k) VnT[(cq * 16 + k) * QLD + s] = f2bf(v[k] * rs); }
;         BLOCK_SYNC();
;         { const int t = 16 * wave + fr; f32x4 y[4]; float ss = 0.f;
;           const float bias = a.in[I_SB][((size_t)layer * 4 + grp) * 128 + t];
;           const bf16* ur = z + (t0 + t) * DIN + ZU + grp * 64;
; #pragma unroll
;           for (int cb = 0; cb < 4; ++cb) { f32x4 acc = (f32x4){0.f, 0.f, 0.f, 0.f};
;               acc = mma16<4>(Wm + 16 * wave * QLD, QLD, VnT + 16 * cb * QLD, QLD, acc, fr, fq);
;               const u32x2 uw = *(const u32x2*)(ur + 16 * cb + 4 * fq);
;               const float u0 = __uint_as_float(uw.x << 16), u1 = __uint_as_float(uw.x & 0xffff0000u), u2 = __uint_as_float(uw.y << 16), u3 = __uint_as_float(uw.y & 0xffff0000u);
;               y[cb] = (f32x4){gelu_t(u0) * (acc[0] + bias), gelu_t(u1) * (acc[1] + bias), gelu_t(u2) * (acc[2] + bias), gelu_t(u3) * (acc[3] + bias)};
	v_add_f32_e32 v41, v41, v42
	ds_bpermute_b32 v42, v69, v41
	s_waitcnt lgkmcnt(0)
	v_add_f32_e32 v41, v41, v42
	v_mul_f32_e32 v42, 0x3c800000, v41
	v_fma_f32 v41, v14, v13, -v42
	v_fma_f32 v0, v12, v0, -v42
	v_mul_f32_e32 v14, v41, v41
	v_fmac_f32_e32 v14, v0, v0
	v_fma_f32 v16, v16, v15, -v42
	v_fmac_f32_e32 v14, v16, v16
	v_fma_f32 v17, v18, v17, -v42
	v_fmac_f32_e32 v14, v17, v17
	v_fma_f32 v18, v20, v19, -v42
	v_fmac_f32_e32 v14, v18, v18
	v_fma_f32 v19, v22, v21, -v42
	v_fmac_f32_e32 v14, v19, v19
	v_fma_f32 v20, v24, v23, -v42
	v_fmac_f32_e32 v14, v20, v20
	v_fma_f32 v21, v39, v25, -v42
	v_pk_fma_f32 v[2:3], v[2:3], v[54:55], v[42:43] op_sel_hi:[1,1,0] neg_lo:[0,0,1] neg_hi:[0,0,1]
	v_fmac_f32_e32 v14, v21, v21
	v_pk_mul_f32 v[12:13], v[2:3], v[2:3]
	v_pk_fma_f32 v[4:5], v[4:5], v[44:45], v[42:43] op_sel_hi:[1,1,0] neg_lo:[0,0,1] neg_hi:[0,0,1]
	v_add_f32_e32 v13, v13, v14
	v_add_f32_e32 v22, v12, v13
	v_pk_fma_f32 v[12:13], v[50:51], v[48:49], v[42:43] op_sel_hi:[1,1,0] neg_lo:[0,0,1] neg_hi:[0,0,1]
	v_pk_fma_f32 v[8:9], v[10:11], v[8:9], v[42:43] op_sel_hi:[1,1,0] neg_lo:[0,0,1] neg_hi:[0,0,1]
	v_pk_mul_f32 v[14:15], v[12:13], v[12:13]
	v_pk_mul_f32 v[10:11], v[8:9], v[8:9]
	v_add_f32_e32 v15, v15, v22
	v_add_f32_e32 v22, v14, v15
	v_pk_mul_f32 v[14:15], v[4:5], v[4:5]
	v_lshl_add_u64 v[48:49], s[8:9], 0, v[28:29]
	v_add_f32_e32 v15, v15, v22
	v_add_f32_e32 v14, v14, v15
	v_add_f32_e32 v11, v11, v14
	v_add_f32_e32 v10, v10, v11
	ds_bpermute_b32 v11, v68, v10
	s_waitcnt lgkmcnt(0)
	v_add_f32_e32 v10, v10, v11
	ds_bpermute_b32 v11, v69, v10
	s_waitcnt lgkmcnt(0)
	v_add_f32_e32 v10, v10, v11
	v_fmamk_f32 v10, v10, 0x3c800000, v142
	v_cmp_gt_f32_e32 vcc, s72, v10
	v_mul_f32_e32 v11, 0x4b800000, v10
	s_nop 0
	v_cndmask_b32_e32 v10, v10, v11, vcc
	v_rsq_f32_e32 v10, v10
	s_nop 0
	v_mul_f32_e32 v11, 0x45800000, v10
	v_cndmask_b32_e32 v10, v10, v11, vcc
	v_mul_f32_e32 v0, v0, v10
	v_cvt_pk_bf16_f32 v0, v0, s0
	ds_write_b16 v72, v0 offset:34816
	v_mul_f32_e32 v0, v41, v10
	v_cvt_pk_bf16_f32 v0, v0, s0
	ds_write_b16 v72, v0 offset:35088
	v_mul_f32_e32 v0, v16, v10
	v_cvt_pk_bf16_f32 v0, v0, s0
	ds_write_b16 v72, v0 offset:35360
	v_mul_f32_e32 v0, v17, v10
	v_cvt_pk_bf16_f32 v0, v0, s0
	ds_write_b16 v72, v0 offset:35632
	v_mul_f32_e32 v0, v18, v10
	v_cvt_pk_bf16_f32 v0, v0, s0
	ds_write_b16 v72, v0 offset:35904
	v_mul_f32_e32 v0, v19, v10
	v_cvt_pk_bf16_f32 v0, v0, s0
	ds_write_b16 v72, v0 offset:36176
	v_mul_f32_e32 v0, v20, v10
	v_cvt_pk_bf16_f32 v0, v0, s0
	ds_write_b16 v72, v0 offset:36448
	v_mul_f32_e32 v0, v21, v10
	v_cvt_pk_bf16_f32 v0, v0, s0
	ds_write_b16 v72, v0 offset:36720
	v_mul_f32_e32 v0, v3, v10
	v_cvt_pk_bf16_f32 v0, v0, s0
	ds_write_b16 v72, v0 offset:36992
	v_mul_f32_e32 v0, v2, v10
	v_cvt_pk_bf16_f32 v0, v0, s0
	ds_write_b16 v72, v0 offset:37264
	v_mul_f32_e32 v0, v13, v10
	v_cvt_pk_bf16_f32 v0, v0, s0
	ds_write_b16 v72, v0 offset:37536
	v_mul_f32_e32 v0, v12, v10
	v_cvt_pk_bf16_f32 v0, v0, s0
	ds_write_b16 v72, v0 offset:37808
	v_mul_f32_e32 v0, v5, v10
	v_cvt_pk_bf16_f32 v0, v0, s0
	ds_write_b16 v72, v0 offset:38080
	v_mul_f32_e32 v0, v4, v10
	v_cvt_pk_bf16_f32 v0, v0, s0
	ds_write_b16 v72, v0 offset:38352
	v_mul_f32_e32 v0, v9, v10
	v_cvt_pk_bf16_f32 v0, v0, s0
	ds_write_b16 v72, v0 offset:38624
	v_mul_f32_e32 v0, v8, v10
	v_cvt_pk_bf16_f32 v0, v0, s0
	ds_write_b16 v72, v0 offset:38896
	s_waitcnt lgkmcnt(0)
	s_barrier
	v_lshl_add_u64 v[2:3], v[30:31], 0, s[12:13]
	global_load_dword v0, v[2:3], off
	v_mad_u64_u32 v[2:3], s[8:9], v48, s60, v[6:7]
	v_mad_i32_i24 v3, v49, s60, v3
	v_lshl_add_u64 v[2:3], v[2:3], 0, s[62:63]
	v_mov_b32_e32 v41, v1
	ds_read_b128 v[22:25], v34
	ds_read_b128 v[18:21], v34 offset:64
	ds_read_b128 v[14:17], v34 offset:128
	ds_read_b128 v[10:13], v34 offset:192
	v_lshl_add_u64 v[42:43], v[2:3], 0, v[40:41]
	ds_read_b128 v[2:5], v32 offset:34816
	ds_read_b128 v[6:9], v32 offset:34880
	s_waitcnt lgkmcnt(1)
	v_mfma_f32_16x16x32_bf16 v[2:5], v[2:5], v[22:25], 0
	ds_read_b128 v[54:57], v32 offset:43584
	ds_read_b128 v[74:77], v32 offset:47872
	s_mov_b64 s[8:9], 0x1400
	s_waitcnt lgkmcnt(2)
	v_mfma_f32_16x16x32_bf16 v[2:5], v[6:9], v[18:21], v[2:5]
	ds_read_b128 v[6:9], v32 offset:34944
	v_lshl_add_u64 v[66:67], v[42:43], 0, s[8:9]
	s_waitcnt lgkmcnt(0)
	v_mfma_f32_16x16x32_bf16 v[2:5], v[6:9], v[14:17], v[2:5]
	ds_read_b128 v[6:9], v32 offset:35008
	s_waitcnt lgkmcnt(0)
	v_mfma_f32_16x16x32_bf16 v[6:9], v[6:9], v[10:13], v[2:5]
	s_nop 4
	v_add_co_u32_e32 v2, vcc, s71, v42
	s_waitcnt vmcnt(0)
	s_nop 0
	v_pk_add_f32 v[8:9], v[0:1], v[8:9] op_sel_hi:[0,1]
	v_addc_co_u32_e32 v3, vcc, 0, v43, vcc
	global_load_dwordx2 v[46:47], v[2:3], off offset:1024
	ds_read_b128 v[2:5], v32 offset:39168
	ds_read_b128 v[42:45], v32 offset:39232
	s_waitcnt lgkmcnt(1)
	v_mfma_f32_16x16x32_bf16 v[2:5], v[2:5], v[22:25], 0
	v_add_f32_e64 v6, v0, v6
	v_add_f32_e64 v7, v0, v7
	s_waitcnt lgkmcnt(0)
	v_mfma_f32_16x16x32_bf16 v[2:5], v[42:45], v[18:21], v[2:5]
	ds_read_b128 v[42:45], v32 offset:39296
	s_waitcnt lgkmcnt(0)
	v_mfma_f32_16x16x32_bf16 v[2:5], v[42:45], v[14:17], v[2:5]
	ds_read_b128 v[42:45], v32 offset:39360
	s_waitcnt lgkmcnt(0)
	v_mfma_f32_16x16x32_bf16 v[2:5], v[42:45], v[10:13], v[2:5]
	global_load_dwordx2 v[44:45], v[66:67], off offset:32
	s_nop 6
	v_pk_add_f32 v[2:3], v[0:1], v[2:3] op_sel_hi:[0,1]
	v_pk_add_f32 v[4:5], v[0:1], v[4:5] op_sel_hi:[0,1]
	s_waitcnt vmcnt(0)
; __device__ __forceinline__ float gelu_t(float x) { return x * fsigmoid(1.5957691216f * (x + 0.044715f * x * x * x)); }
; __device__ __forceinline__ void sgu_items(CArgs& a, LAS unsigned char* lds, int layer, int first, int stride, const bf16* z, bf16* mix) {
;     ...
;         { const int t = 16 * wave + fr; f32x4 y[4]; float ss = 0.f;
;           const float bias = a.in[I_SB][((size_t)layer * 4 + grp) * 128 + t];
;           const bf16* ur = z + (t0 + t) * DIN + ZU + grp * 64;
; #pragma unroll
;           for (int cb = 0; cb < 4; ++cb) { f32x4 acc = (f32x4){0.f, 0.f, 0.f, 0.f};
;               acc = mma16<4>(Wm + 16 * wave * QLD, QLD, VnT + 16 * cb * QLD, QLD, acc, fr, fq);
;               const u32x2 uw = *(const u32x2*)(ur + 16 * cb + 4 * fq);
;               const float u0 = __uint_as_float(uw.x << 16), u1 = __uint_as_float(uw.x & 0xffff0000u), u2 = __uint_as_float(uw.y << 16), u3 = __uint_as_float(uw.y & 0xffff0000u);
;               y[cb] = (f32x4){gelu_t(u0) * (acc[0] + bias), gelu_t(u1) * (acc[1] + bias), gelu_t(u2) * (acc[2] + bias), gelu_t(u3) * (acc[3] + bias)};
;               ss += (y[cb][0] * y[cb][0] + y[cb][1] * y[cb][1]) + (y[cb][2] * y[cb][2] + y[cb][3] * y[cb][3]); }
	v_lshlrev_b32_e32 v42, 16, v45
	v_mul_f32_e32 v39, 0x3d372713, v42
	v_and_b32_e32 v43, 0xffff0000, v45
	v_mul_f32_e32 v39, v39, v42
	v_mov_b32_e32 v45, v42
	v_fmac_f32_e32 v45, v39, v45
	v_mul_f32_e32 v39, 0x3fcc422a, v45
	v_mul_f32_e32 v39, 0xbfb8aa3b, v39
	v_exp_f32_e32 v39, v39
	v_mov_b32_e32 v45, v43
	v_add_f32_e32 v39, 1.0, v39
	v_rcp_f32_e32 v50, v39
	v_mul_f32_e32 v39, 0x3d372713, v43
	v_mul_f32_e32 v39, v39, v43
	v_fmac_f32_e32 v45, v39, v45
	v_mul_f32_e32 v39, 0x3fcc422a, v45
	v_mul_f32_e32 v39, 0xbfb8aa3b, v39
	v_exp_f32_e32 v39, v39
	s_nop 0
	v_add_f32_e32 v39, 1.0, v39
	v_rcp_f32_e32 v51, v39
	s_nop 0
	v_pk_mul_f32 v[42:43], v[50:51], v[42:43]
	ds_read_b128 v[50:53], v32 offset:43520
	s_waitcnt lgkmcnt(0)
	v_mfma_f32_16x16x32_bf16 v[50:53], v[50:53], v[22:25], 0
	v_mul_f32_e64 v4, v4, v42
	v_mul_f32_e64 v5, v5, v43
	v_mul_f32_e32 v42, v5, v5
	v_mfma_f32_16x16x32_bf16 v[50:53], v[54:57], v[18:21], v[50:53]
	ds_read_b128 v[54:57], v32 offset:43648
	v_pk_fma_f32 v[42:43], v[4:5], v[4:5], v[42:43] op_sel_hi:[1,1,0]
	v_mfma_f32_16x16x32_bf16 v[22:25], v[74:77], v[22:25], 0
	ds_read_b128 v[74:77], v32 offset:47936
	s_waitcnt lgkmcnt(1)
	v_mfma_f32_16x16x32_bf16 v[50:53], v[54:57], v[14:17], v[50:53]
	ds_read_b128 v[54:57], v32 offset:43712
	s_waitcnt lgkmcnt(1)
	v_mfma_f32_16x16x32_bf16 v[18:21], v[74:77], v[18:21], v[22:25]
	s_nop 2
	ds_read_b128 v[22:25], v32 offset:48000
	s_waitcnt lgkmcnt(1)
	v_mfma_f32_16x16x32_bf16 v[54:57], v[54:57], v[10:13], v[50:53]
	s_nop 2
	global_load_dwordx2 v[50:51], v[66:67], off offset:64
	s_waitcnt lgkmcnt(0)
	v_mfma_f32_16x16x32_bf16 v[14:17], v[22:25], v[14:17], v[18:21]
	s_nop 2
	ds_read_b128 v[18:21], v32 offset:48064
	v_add_f32_e32 v60, v0, v55
	v_add_f32_e32 v64, v0, v57
	s_waitcnt lgkmcnt(0)
	v_mfma_f32_16x16x32_bf16 v[10:13], v[18:21], v[10:13], v[14:17]
	s_nop 2
	global_load_dwordx2 v[16:17], v[66:67], off offset:96
	v_add_f32_e32 v54, v0, v54
	v_add_f32_e32 v56, v0, v56
	s_nop 1
	v_add_f32_e32 v20, v0, v10
	v_add_f32_e32 v21, v0, v11
	v_add_f32_e32 v75, v0, v12
	v_add_f32_e32 v77, v0, v13
	s_waitcnt vmcnt(1)
	v_lshlrev_b32_e32 v39, 16, v50
	v_and_b32_e32 v45, 0xffff0000, v50
	v_mul_f32_e32 v50, 0x3d372713, v39
	v_mul_f32_e32 v50, v50, v39
	v_fma_f32 v50, v50, v39, v39
	v_mul_f32_e32 v50, 0x3fcc422a, v50
	v_mul_f32_e32 v50, 0xbfb8aa3b, v50
	v_exp_f32_e32 v50, v50
	v_lshlrev_b32_e32 v52, 16, v51
	v_and_b32_e32 v51, 0xffff0000, v51
	v_add_f32_e32 v50, 1.0, v50
	v_rcp_f32_e32 v50, v50
	s_waitcnt vmcnt(0)
	v_and_b32_e32 v15, 0xffff0000, v16
	v_mul_f32_e32 v50, v50, v39
	v_mul_f32_e32 v39, 0x3d372713, v45
	v_mul_f32_e32 v39, v39, v45
	v_fma_f32 v39, v39, v45, v45
	v_mul_f32_e32 v39, 0x3fcc422a, v39
	v_mul_f32_e32 v39, 0xbfb8aa3b, v39
	v_exp_f32_e32 v39, v39
	v_mul_f32_e32 v10, 0x3d372713, v15
	v_mul_f32_e32 v10, v10, v15
	v_fma_f32 v10, v10, v15, v15
	v_add_f32_e32 v39, 1.0, v39
	v_rcp_f32_e32 v39, v39
	v_mul_f32_e32 v10, 0x3fcc422a, v10
	v_mul_f32_e32 v10, 0xbfb8aa3b, v10
	v_exp_f32_e32 v10, v10
	v_mul_f32_e32 v58, v39, v45
	v_mul_f32_e32 v39, 0x3d372713, v52
	v_mul_f32_e32 v39, v39, v52
	v_fma_f32 v39, v39, v52, v52
	v_mul_f32_e32 v39, 0x3fcc422a, v39
	v_mul_f32_e32 v39, 0xbfb8aa3b, v39
	v_exp_f32_e32 v39, v39
	v_add_f32_e32 v10, 1.0, v10
	v_rcp_f32_e32 v23, v10
	v_and_b32_e32 v53, 0xffff0000, v17
	v_add_f32_e32 v39, 1.0, v39
	v_rcp_f32_e32 v39, v39
	v_lshlrev_b32_e32 v25, 16, v16
	v_mul_f32_e32 v14, 0x3d372713, v25
	v_mul_f32_e32 v14, v14, v25
	v_mul_f32_e32 v52, v39, v52
	v_mul_f32_e32 v39, 0x3d372713, v51
	v_mul_f32_e32 v39, v39, v51
	v_fma_f32 v39, v39, v51, v51
	v_mul_f32_e32 v39, 0x3fcc422a, v39
	v_mul_f32_e32 v39, 0xbfb8aa3b, v39
	v_exp_f32_e32 v39, v39
	v_fma_f32 v14, v14, v25, v25
	v_mul_f32_e32 v14, 0x3fcc422a, v14
	v_mul_f32_e32 v14, 0xbfb8aa3b, v14
	v_add_f32_e32 v39, 1.0, v39
	v_rcp_f32_e32 v39, v39
	v_exp_f32_e32 v14, v14
	v_mov_b32_e32 v63, v53
	v_mul_f32_e32 v62, v39, v51
	v_lshlrev_b32_e32 v51, 16, v17
	v_mul_f32_e32 v10, 0x3d372713, v51
	v_mul_f32_e32 v10, v10, v51
	v_fma_f32 v10, v10, v51, v51
	v_mul_f32_e32 v10, 0x3fcc422a, v10
	v_mul_f32_e32 v10, 0xbfb8aa3b, v10
	v_exp_f32_e32 v10, v10
	v_add_f32_e32 v14, 1.0, v14
	v_rcp_f32_e32 v67, v14
	v_mov_b32_e32 v59, v51
	v_add_f32_e32 v10, 1.0, v10
	v_rcp_f32_e32 v55, v10
	v_mul_f32_e32 v10, 0x3d372713, v53
	v_mul_f32_e32 v10, v10, v53
	v_fma_f32 v10, v10, v53, v53
	v_mul_f32_e32 v10, 0x3fcc422a, v10
	v_mul_f32_e32 v10, 0xbfb8aa3b, v10
	v_exp_f32_e32 v10, v10
	v_mov_b32_e32 v61, v55
	v_add_f32_e32 v10, 1.0, v10
	v_rcp_f32_e32 v57, v10
	v_lshlrev_b64 v[10:11], 11, v[48:49]
	v_lshlrev_b32_e32 v48, 16, v47
	v_mul_f32_e32 v14, 0x3d372713, v48
	v_mul_f32_e32 v14, v14, v48
	v_mov_b32_e32 v22, v48
	v_fmac_f32_e32 v22, v14, v22
	v_mul_f32_e32 v14, 0x3fcc422a, v22
	v_mul_f32_e32 v14, 0xbfb8aa3b, v14
	v_exp_f32_e32 v14, v14
	v_and_b32_e32 v49, 0xffff0000, v47
	v_mov_b32_e32 v22, v49
	v_lshl_add_u64 v[10:11], s[92:93], 0, v[10:11]
	v_add_f32_e32 v14, 1.0, v14
	v_rcp_f32_e32 v78, v14
	v_mul_f32_e32 v14, 0x3d372713, v49
	v_mul_f32_e32 v14, v14, v49
	v_fmac_f32_e32 v22, v14, v22
	v_mul_f32_e32 v14, 0x3fcc422a, v22
	v_mul_f32_e32 v14, 0xbfb8aa3b, v14
	v_exp_f32_e32 v14, v14
	v_lshl_add_u64 v[10:11], v[10:11], 0, s[62:63]
	s_lshl_b32 s62, s15, 8
	v_lshl_add_u64 v[18:19], v[36:37], 0, s[62:63]
; __device__ __forceinline__ unsigned cvt_pk_bf16(float lo, float hi) { f32x2_t v = {lo, hi}; bf16x2_t b = __builtin_convertvector(v, bf16x2_t); return __builtin_bit_cast(unsigned, b); }
; __device__ __forceinline__ float gelu_t(float x) { return x * fsigmoid(1.5957691216f * (x + 0.044715f * x * x * x)); }
; __device__ __forceinline__ void sgu_items(CArgs& a, LAS unsigned char* lds, int layer, int first, int stride, const bf16* z, bf16* mix) {
;     ...
;               y[cb] = (f32x4){gelu_t(u0) * (acc[0] + bias), gelu_t(u1) * (acc[1] + bias), gelu_t(u2) * (acc[2] + bias), gelu_t(u3) * (acc[3] + bias)};
;               ss += (y[cb][0] * y[cb][0] + y[cb][1] * y[cb][1]) + (y[cb][2] * y[cb][2] + y[cb][3] * y[cb][3]); }
;           ss += __shfl_xor(ss, 16); ss += __shfl_xor(ss, 32);
;           const float rs = SG_SCALE * rsqrtf(ss * (1.f / 64.f) + EPS);
;           const float* ng = a.in[I_SN] + layer * 256 + grp * 64; bf16* mr = mix + (t0 + t) * D + 768 + grp * 64;
; #pragma unroll
;           for (int cb = 0; cb < 4; ++cb) { const f32x4 gg = *(const f32x4*)(ng + 16 * cb + 4 * fq);
;               u32x2 w; w.x = cvt_pk_bf16(y[cb][0] * rs * gg[0], y[cb][1] * rs * gg[1]); w.y = cvt_pk_bf16(y[cb][2] * rs * gg[2], y[cb][3] * rs * gg[3]);
;               *(u32x2*)(mr + 16 * cb + 4 * fq) = w; } }
	v_add_f32_e32 v14, 1.0, v14
	v_rcp_f32_e32 v79, v14
	v_lshl_add_u64 v[16:17], v[10:11], 0, v[40:41]
	global_load_dwordx4 v[10:13], v[18:19], off
	global_load_dwordx4 v[84:87], v[18:19], off offset:64
	global_load_dwordx4 v[88:91], v[18:19], off offset:128
	global_load_dwordx4 v[92:95], v[18:19], off offset:192
	v_mov_b32_e32 v65, v57
	v_pk_mul_f32 v[48:49], v[78:79], v[48:49]
	v_lshlrev_b32_e32 v78, 16, v46
	v_pk_mul_f32 v[8:9], v[8:9], v[48:49]
	v_mov_b32_e32 v22, v78
	v_mul_f32_e32 v14, v9, v9
	v_pk_fma_f32 v[48:49], v[8:9], v[8:9], v[14:15] op_sel_hi:[1,1,0]
	v_mul_f32_e32 v14, 0x3d372713, v78
	v_mul_f32_e32 v14, v14, v78
	v_fmac_f32_e32 v22, v14, v22
	v_mul_f32_e32 v14, 0x3fcc422a, v22
	v_mul_f32_e32 v14, 0xbfb8aa3b, v14
	v_exp_f32_e32 v14, v14
	v_and_b32_e32 v79, 0xffff0000, v46
	v_mov_b32_e32 v22, v79
	s_cmpk_gt_i32 s14, 0x3ff
	v_add_f32_e32 v14, 1.0, v14
	v_rcp_f32_e32 v46, v14
	v_mul_f32_e32 v14, 0x3d372713, v79
	v_mul_f32_e32 v14, v14, v79
	v_fmac_f32_e32 v22, v14, v22
	v_mul_f32_e32 v14, 0x3fcc422a, v22
	v_mul_f32_e32 v14, 0xbfb8aa3b, v14
	v_exp_f32_e32 v14, v14
	s_nop 0
	v_add_f32_e32 v14, 1.0, v14
	v_rcp_f32_e32 v47, v14
	s_nop 0
	v_pk_mul_f32 v[46:47], v[46:47], v[78:79]
	v_pk_mul_f32 v[78:79], v[54:55], v[50:51]
	v_pk_mul_f32 v[50:51], v[60:61], v[58:59]
	v_mov_b32_e32 v74, v78
	v_pk_mul_f32 v[60:61], v[56:57], v[52:53]
	v_pk_mul_f32 v[54:55], v[78:79], v[74:75]
	v_mov_b32_e32 v74, v50
	v_pk_mul_f32 v[52:53], v[64:65], v[62:63]
	v_mov_b32_e32 v76, v60
	v_pk_mul_f32 v[6:7], v[6:7], v[46:47]
	v_pk_mul_f32 v[58:59], v[50:51], v[74:75]
	v_pk_mul_f32 v[56:57], v[60:61], v[76:77]
	v_mov_b32_e32 v76, v52
	v_pk_mul_f32 v[46:47], v[6:7], v[6:7]
	v_pk_mul_f32 v[62:63], v[52:53], v[76:77]
	v_pk_fma_f32 v[64:65], v[50:51], v[74:75], v[54:55]
	v_pk_mul_f32 v[58:59], v[54:55], v[58:59]
	v_mov_b32_e32 v66, v7
	v_mov_b32_e32 v24, v7
	v_mov_b32_e32 v65, v59
	v_pk_fma_f32 v[58:59], v[52:53], v[76:77], v[56:57]
	v_pk_mul_f32 v[62:63], v[56:57], v[62:63]
	v_pk_mul_f32 v[24:25], v[66:67], v[24:25]
	v_mov_b32_e32 v47, v20
	v_mov_b32_e32 v59, v63
	v_pk_fma_f32 v[62:63], v[6:7], v[6:7], v[24:25]
	v_pk_mul_f32 v[24:25], v[46:47], v[24:25]
	v_pk_add_f32 v[46:47], v[62:63], v[48:49]
	v_pk_mul_f32 v[48:49], v[24:25], v[24:25]
	v_pk_add_f32 v[58:59], v[64:65], v[58:59]
	v_lshlrev_b32_e32 v48, 16, v44
	v_mul_f32_e32 v14, 0x3d372713, v48
	v_mul_f32_e32 v14, v14, v48
	v_mov_b32_e32 v20, v48
	v_fmac_f32_e32 v20, v14, v20
	v_mul_f32_e32 v14, 0x3fcc422a, v20
	v_mul_f32_e32 v14, 0xbfb8aa3b, v14
	v_exp_f32_e32 v14, v14
	v_mov_b32_e32 v47, v49
	v_and_b32_e32 v49, 0xffff0000, v44
	v_mov_b32_e32 v20, v49
	v_add_f32_e32 v14, 1.0, v14
	v_rcp_f32_e32 v44, v14
	v_mul_f32_e32 v14, 0x3d372713, v49
	v_mul_f32_e32 v14, v14, v49
	v_fmac_f32_e32 v20, v14, v20
	v_mul_f32_e32 v14, 0x3fcc422a, v20
	v_mul_f32_e32 v14, 0xbfb8aa3b, v14
	v_exp_f32_e32 v14, v14
	v_mov_b32_e32 v79, v50
	v_mov_b32_e32 v61, v52
	v_mov_b32_e32 v56, v55
	v_add_f32_e32 v14, 1.0, v14
	v_rcp_f32_e32 v45, v14
	s_nop 0
	v_pk_mul_f32 v[44:45], v[44:45], v[48:49]
	s_nop 0
	v_pk_mul_f32 v[2:3], v[2:3], v[44:45]
	s_nop 0
	v_mov_b32_e32 v22, v2
	v_mov_b32_e32 v14, v2
	v_pk_mul_f32 v[44:45], v[22:23], v[14:15]
	v_mul_f32_e32 v20, v3, v3
	v_pk_fma_f32 v[14:15], v[22:23], v[14:15], v[20:21] op_sel_hi:[1,1,0]
	v_pk_mul_f32 v[20:21], v[44:45], v[20:21]
	v_pk_add_f32 v[14:15], v[14:15], v[42:43]
	v_pk_mul_f32 v[22:23], v[20:21], v[20:21]
	v_mov_b32_e32 v20, v25
	v_mov_b32_e32 v15, v23
	v_pk_add_f32 v[14:15], v[46:47], v[14:15]
	s_nop 0
	v_pk_add_f32 v[14:15], v[14:15], v[58:59]
	s_nop 0
	v_add_f32_e32 v0, v14, v15
	ds_bpermute_b32 v14, v35, v0
	s_waitcnt lgkmcnt(0)
	v_add_f32_e32 v0, v0, v14
	ds_bpermute_b32 v14, v70, v0
	s_waitcnt lgkmcnt(0)
	v_add_f32_e32 v0, v0, v14
	v_fmamk_f32 v0, v0, 0x3c800000, v142
	v_cmp_gt_f32_e32 vcc, s72, v0
	v_mul_f32_e32 v14, 0x4b800000, v0
	s_nop 0
	v_cndmask_b32_e32 v0, v0, v14, vcc
	v_rsq_f32_e32 v0, v0
	s_nop 0
	v_mul_f32_e32 v14, 0x45800000, v0
	v_cndmask_b32_e32 v0, v0, v14, vcc
	v_pk_mul_f32 v[6:7], v[6:7], v[0:1] op_sel_hi:[1,0]
	v_pk_mul_f32 v[8:9], v[8:9], v[0:1] op_sel_hi:[1,0]
	s_waitcnt vmcnt(0)
	v_pk_mul_f32 v[6:7], v[10:11], v[6:7]
	v_pk_mul_f32 v[8:9], v[12:13], v[8:9]
	v_cvt_pk_bf16_f32 v6, v6, v7
	v_cvt_pk_bf16_f32 v7, v8, v9
	global_store_dwordx2 v[16:17], v[6:7], off offset:1536
	v_pk_mul_f32 v[2:3], v[2:3], v[0:1] op_sel_hi:[1,0]
	v_pk_mul_f32 v[4:5], v[4:5], v[0:1] op_sel_hi:[1,0]
	v_pk_mul_f32 v[2:3], v[84:85], v[2:3]
	v_pk_mul_f32 v[4:5], v[86:87], v[4:5]
	v_cvt_pk_bf16_f32 v2, v2, v3
	v_cvt_pk_bf16_f32 v3, v4, v5
	global_store_dwordx2 v[16:17], v[2:3], off offset:1568
	v_pk_mul_f32 v[6:7], v[78:79], v[0:1] op_sel_hi:[1,0]
	v_pk_mul_f32 v[2:3], v[88:89], v[6:7]
	v_pk_mul_f32 v[6:7], v[60:61], v[0:1] op_sel_hi:[1,0]
	v_cvt_pk_bf16_f32 v2, v2, v3
	v_pk_mul_f32 v[4:5], v[90:91], v[6:7]
	v_pk_mul_f32 v[6:7], v[20:21], v[0:1] op_sel_hi:[1,0]
	v_cvt_pk_bf16_f32 v3, v4, v5
	global_store_dwordx2 v[16:17], v[2:3], off offset:1600
	v_pk_mul_f32 v[2:3], v[92:93], v[6:7]
	v_pk_mul_f32 v[6:7], v[56:57], v[0:1] op_sel_hi:[1,0]
	v_cvt_pk_bf16_f32 v2, v2, v3
	v_pk_mul_f32 v[4:5], v[94:95], v[6:7]
	s_nop 0
	v_cvt_pk_bf16_f32 v3, v4, v5
	global_store_dwordx2 v[16:17], v[2:3], off offset:1632
	s_waitcnt lgkmcnt(0)
	s_barrier
	s_cbranch_scc1 .LBB0_215

; __device__ __forceinline__ unsigned cvt_pk_bf16(float lo, float hi) { f32x2_t v = {lo, hi}; bf16x2_t b = __builtin_convertvector(v, bf16x2_t); return __builtin_bit_cast(unsigned, b); }
; #define LAS __attribute__((address_space(3)))
; __device__ __forceinline__ void sgu_items(CArgs& a, LAS unsigned char* lds, int layer, int first, int stride, const bf16* z, bf16* mix) {
;     ...
;         if (grp != cur_grp) { cur_grp = grp;
;             const float* ws = a.in[I_SW] + ((size_t)layer * 4 + grp) * 16384;
;             for (int e = tid; e < 4096; e += NTHREADS) { const int t = e >> 5, s0 = (e & 31) * 4; const f32x4 wv = *(const f32x4*)(ws + t * 128 + s0);
;                 u32x2 w; w.x = cvt_pk_bf16(s0 <= t ? wv[0] : 0.f, s0 + 1 <= t ? wv[1] : 0.f); w.y = cvt_pk_bf16(s0 + 2 <= t ? wv[2] : 0.f, s0 + 3 <= t ? wv[3] : 0.f);
;                 *(LAS u32x2*)(Wm + t * QLD + s0) = w; } }
.LBB0_214:
	v_ashrrev_i32_e32 v8, 5, v3
	v_lshlrev_b32_e32 v4, 7, v8
	v_and_b32_e32 v9, 0x7c, v2
	v_ashrrev_i32_e32 v5, 31, v4
	v_lshl_add_u64 v[4:5], v[4:5], 2, s[10:11]
	v_lshlrev_b32_e32 v0, 2, v9
	v_lshl_add_u64 v[4:5], v[4:5], 0, v[0:1]
	s_mov_b64 s[12:13], 0x2000
	global_load_dwordx4 v[44:47], v[4:5], off
	v_lshl_add_u64 v[4:5], v[4:5], 0, s[12:13]
	global_load_dwordx4 v[48:51], v[4:5], off
	v_lshl_add_u64 v[4:5], v[4:5], 0, s[12:13]
	global_load_dwordx4 v[52:55], v[4:5], off
	v_lshl_add_u64 v[4:5], v[4:5], 0, s[12:13]
	global_load_dwordx4 v[56:59], v[4:5], off
	v_lshl_add_u64 v[4:5], v[4:5], 0, s[12:13]
	global_load_dwordx4 v[60:63], v[4:5], off
	v_lshl_add_u64 v[4:5], v[4:5], 0, s[12:13]
	global_load_dwordx4 v[64:67], v[4:5], off
	v_lshl_add_u64 v[4:5], v[4:5], 0, s[12:13]
	global_load_dwordx4 v[74:77], v[4:5], off
	v_lshl_add_u64 v[4:5], v[4:5], 0, s[12:13]
	global_load_dwordx4 v[78:81], v[4:5], off
	v_mul_lo_u32 v0, v8, s4
	v_lshlrev_b32_e32 v6, 1, v9
	v_add3_u32 v0, 0, v0, v6
	v_or_b32_e32 v6, 2, v9
	v_or_b32_e32 v5, 3, v9
	v_add_u32_e32 v7, 0, v8
	s_waitcnt vmcnt(7)
	v_cmp_le_i32_e32 vcc, v9, v7
	s_nop 1
	v_cndmask_b32_e32 v2, 0, v44, vcc
	v_cmp_lt_i32_e32 vcc, v9, v7
	s_nop 1
	v_cndmask_b32_e32 v3, 0, v45, vcc
	v_cvt_pk_bf16_f32 v2, v2, v3
	v_cmp_le_i32_e32 vcc, v6, v7
	s_nop 1
	v_cndmask_b32_e32 v3, 0, v46, vcc
	v_cmp_le_i32_e32 vcc, v5, v7
	s_nop 1
	v_cndmask_b32_e32 v4, 0, v47, vcc
	v_cvt_pk_bf16_f32 v3, v3, v4
	ds_write_b64 v0, v[2:3]
	v_add_u32_e32 v7, 16, v8
	s_waitcnt vmcnt(6)
	v_cmp_le_i32_e32 vcc, v9, v7
	s_nop 1
	v_cndmask_b32_e32 v2, 0, v48, vcc
	v_cmp_lt_i32_e32 vcc, v9, v7
	s_nop 1
	v_cndmask_b32_e32 v3, 0, v49, vcc
	v_cvt_pk_bf16_f32 v2, v2, v3
	v_cmp_le_i32_e32 vcc, v6, v7
	s_nop 1
	v_cndmask_b32_e32 v3, 0, v50, vcc
	v_cmp_le_i32_e32 vcc, v5, v7
	s_nop 1
	v_cndmask_b32_e32 v4, 0, v51, vcc
	v_cvt_pk_bf16_f32 v3, v3, v4
	ds_write_b64 v0, v[2:3] offset:4352
	v_add_u32_e32 v7, 32, v8
	s_waitcnt vmcnt(5)
	v_cmp_le_i32_e32 vcc, v9, v7
	s_nop 1
	v_cndmask_b32_e32 v2, 0, v52, vcc
	v_cmp_lt_i32_e32 vcc, v9, v7
	s_nop 1
	v_cndmask_b32_e32 v3, 0, v53, vcc
	v_cvt_pk_bf16_f32 v2, v2, v3
	v_cmp_le_i32_e32 vcc, v6, v7
	s_nop 1
	v_cndmask_b32_e32 v3, 0, v54, vcc
	v_cmp_le_i32_e32 vcc, v5, v7
	s_nop 1
	v_cndmask_b32_e32 v4, 0, v55, vcc
	v_cvt_pk_bf16_f32 v3, v3, v4
	ds_write_b64 v0, v[2:3] offset:8704
	v_add_u32_e32 v7, 48, v8
	s_waitcnt vmcnt(4)
	v_cmp_le_i32_e32 vcc, v9, v7
	s_nop 1
	v_cndmask_b32_e32 v2, 0, v56, vcc
	v_cmp_lt_i32_e32 vcc, v9, v7
	s_nop 1
	v_cndmask_b32_e32 v3, 0, v57, vcc
	v_cvt_pk_bf16_f32 v2, v2, v3
	v_cmp_le_i32_e32 vcc, v6, v7
	s_nop 1
	v_cndmask_b32_e32 v3, 0, v58, vcc
	v_cmp_le_i32_e32 vcc, v5, v7
	s_nop 1
	v_cndmask_b32_e32 v4, 0, v59, vcc
	v_cvt_pk_bf16_f32 v3, v3, v4
	ds_write_b64 v0, v[2:3] offset:13056
	v_add_u32_e32 v7, 64, v8
	s_waitcnt vmcnt(3)
	v_cmp_le_i32_e32 vcc, v9, v7
	s_nop 1
	v_cndmask_b32_e32 v2, 0, v60, vcc
	v_cmp_lt_i32_e32 vcc, v9, v7
	s_nop 1
	v_cndmask_b32_e32 v3, 0, v61, vcc
	v_cvt_pk_bf16_f32 v2, v2, v3
	v_cmp_le_i32_e32 vcc, v6, v7
	s_nop 1
	v_cndmask_b32_e32 v3, 0, v62, vcc
	v_cmp_le_i32_e32 vcc, v5, v7
	s_nop 1
	v_cndmask_b32_e32 v4, 0, v63, vcc
	v_cvt_pk_bf16_f32 v3, v3, v4
	ds_write_b64 v0, v[2:3] offset:17408
	v_add_u32_e32 v7, 80, v8
	s_waitcnt vmcnt(2)
	v_cmp_le_i32_e32 vcc, v9, v7
	s_nop 1
	v_cndmask_b32_e32 v2, 0, v64, vcc
	v_cmp_lt_i32_e32 vcc, v9, v7
	s_nop 1
	v_cndmask_b32_e32 v3, 0, v65, vcc
	v_cvt_pk_bf16_f32 v2, v2, v3
	v_cmp_le_i32_e32 vcc, v6, v7
	s_nop 1
	v_cndmask_b32_e32 v3, 0, v66, vcc
	v_cmp_le_i32_e32 vcc, v5, v7
	s_nop 1
	v_cndmask_b32_e32 v4, 0, v67, vcc
	v_cvt_pk_bf16_f32 v3, v3, v4
	ds_write_b64 v0, v[2:3] offset:21760
	v_add_u32_e32 v7, 96, v8
	s_waitcnt vmcnt(1)
	v_cmp_le_i32_e32 vcc, v9, v7
	s_nop 1
	v_cndmask_b32_e32 v2, 0, v74, vcc
	v_cmp_lt_i32_e32 vcc, v9, v7
	s_nop 1
	v_cndmask_b32_e32 v3, 0, v75, vcc
	v_cvt_pk_bf16_f32 v2, v2, v3
	v_cmp_le_i32_e32 vcc, v6, v7
	s_nop 1
	v_cndmask_b32_e32 v3, 0, v76, vcc
	v_cmp_le_i32_e32 vcc, v5, v7
	s_nop 1
	v_cndmask_b32_e32 v4, 0, v77, vcc
	v_cvt_pk_bf16_f32 v3, v3, v4
	ds_write_b64 v0, v[2:3] offset:26112
	v_add_u32_e32 v7, 112, v8
	s_waitcnt vmcnt(0)
	v_cmp_le_i32_e32 vcc, v9, v7
	s_nop 1
	v_cndmask_b32_e32 v2, 0, v78, vcc
	v_cmp_lt_i32_e32 vcc, v9, v7
	s_nop 1
	v_cndmask_b32_e32 v3, 0, v79, vcc
	v_cvt_pk_bf16_f32 v2, v2, v3
	v_cmp_le_i32_e32 vcc, v6, v7
	s_nop 1
	v_cndmask_b32_e32 v3, 0, v80, vcc
	v_cmp_le_i32_e32 vcc, v5, v7
	s_nop 1
	v_cndmask_b32_e32 v4, 0, v81, vcc
	v_cvt_pk_bf16_f32 v3, v3, v4
	ds_write_b64 v0, v[2:3] offset:30464
	s_branch .LBB0_209
